# in-proj and out-proj GEMMs: LDS tile image of 8-row x 128-byte blocks so every LDS-DMA fetches whole 128-B lines (was 16 half lines); k=1 fragments read through a second base register
# speedup vs baseline: 1.0627x; 1.0091x over previous
.LBB0_11:
	v_mov_b32_e32 v191, v203
	v_readlane_b32 s6, v254, 10
	v_readfirstlane_b32 s0, v191
	s_ashr_i32 s72, s0, 6
	v_readlane_b32 s0, v254, 6
	v_readlane_b32 s1, v254, 7
	s_waitcnt lgkmcnt(0)
	s_load_dwordx2 s[74:75], s[0:1], 0x80
	s_add_i32 s10, s72, s6
	v_readlane_b32 s6, v254, 11
	v_and_b32_e32 v213, 63, v191
	s_cmp_gt_i32 s16, 0
	v_add_u32_e32 v190, s6, v191
	s_mov_b64 s[6:7], -1
	s_cbranch_scc0 .LBB0_318
	s_add_i32 s6, s16, -1
	s_mul_hi_u32 s7, s6, 0xcccccccd
	v_writelane_b32 v255, s16, 48
	s_lshr_b32 s16, s7, 2
	s_mul_i32 s7, s16, 5
	s_sub_i32 s50, s6, s7
	s_mov_b64 s[6:7], -1
	s_mov_b64 s[8:9], 0
	s_cmp_lt_i32 s50, 2
	s_mov_b64 s[48:49], 0
	s_cbranch_scc1 .LBB0_82
	s_cmp_gt_i32 s50, 2
	s_cbranch_scc0 .LBB0_37
	s_cmp_eq_u32 s50, 3
	s_mov_b64 s[48:49], -1
	s_cbranch_scc0 .LBB0_36
	v_readlane_b32 s6, v254, 12
	v_mov_b32_e32 v8, v203
	v_readlane_b32 s7, v254, 13
	s_andn2_b64 vcc, exec, s[6:7]
	v_readfirstlane_b32 s12, v8
	s_cbranch_vccnz .LBB0_35
	v_lshlrev_b32_e32 v0, 4, v8
	v_add_u32_e32 v1, 0x2000, v0
	v_ashrrev_i32_e32 v2, 31, v1
	v_lshrrev_b32_e32 v2, 22, v2
	v_add_u32_e32 v2, v1, v2
	v_ashrrev_i32_e32 v9, 10, v2
	v_mul_i32_i24_e32 v2, 0x400, v9
	v_sub_u32_e32 v1, v1, v2
	v_lshrrev_b32_e32 v2, 4, v1
	v_bitop3_b32 v1, v2, v1, 32 bitop3:0x6c
	v_ashrrev_i32_e32 v2, 31, v1
	s_waitcnt lgkmcnt(0)
	s_add_u32 s9, s74, 0x1b400000
	v_lshrrev_b32_e32 v2, 26, v2
	s_addc_u32 s11, s75, 0
	s_lshl_b64 s[6:7], s[16:17], 23
	v_add_u32_e32 v2, v1, v2
	v_lshlrev_b32_e32 v3, 3, v9
	s_add_u32 s6, s74, s6
	v_ashrrev_i32_e32 v10, 6, v2
	v_and_b32_e32 v3, -16, v3
	s_addc_u32 s7, s75, s7
	v_add_u32_e32 v3, v10, v3
	s_add_u32 s24, s6, 0x6c00000
	v_and_b32_e32 v4, 3, v10
	s_mov_b32 s6, 0xfffe0
	v_lshrrev_b32_e32 v5, 2, v3
	v_lshlrev_b32_e32 v6, 1, v3
	v_and_b32_e32 v2, 0xc0, v2
	v_and_or_b32 v4, v3, s6, v4
	v_and_b32_e32 v5, 4, v5
	v_and_b32_e32 v6, 24, v6
	v_sub_u32_e32 v1, v1, v2
	v_or3_b32 v4, v4, v5, v6
	v_lshlrev_b32_e32 v5, 5, v9
	v_ashrrev_i16_sdwa v1, v206, sext(v1) dst_sel:DWORD dst_unused:UNUSED_PAD src0_sel:DWORD src1_sel:BYTE_0
	v_and_b32_e32 v5, 32, v5
	v_bfe_i32 v11, v1, 0, 16
	v_add_lshl_u32 v1, v5, v11, 1
	v_lshl_add_u32 v128, v4, 12, v1
	v_lshl_add_u32 v130, v3, 12, v1
	v_bfe_i32 v1, v8, 27, 1
	v_lshrrev_b32_e32 v1, 22, v1
	v_add_u32_e32 v1, v0, v1
	v_and_b32_e32 v1, 0xfffffc00, v1
	v_sub_u32_e32 v0, v0, v1
	v_lshrrev_b32_e32 v1, 4, v0
	v_ashrrev_i32_e32 v2, 31, v8
	v_bitop3_b32 v0, v1, v0, 32 bitop3:0x6c
	v_lshrrev_b32_e32 v2, 26, v2
	v_ashrrev_i32_e32 v1, 31, v0
	v_add_u32_e32 v2, v8, v2
	v_lshrrev_b32_e32 v1, 26, v1
	v_ashrrev_i32_e32 v13, 6, v2
	v_add_u32_e32 v1, v0, v1
	v_lshlrev_b32_e32 v2, 3, v13
	v_ashrrev_i32_e32 v12, 6, v1
	v_and_b32_e32 v2, -16, v2
	v_add_u32_e32 v2, v12, v2
	v_and_b32_e32 v3, 3, v12
	v_lshrrev_b32_e32 v4, 2, v2
	v_lshlrev_b32_e32 v5, 1, v2
	v_and_b32_e32 v1, 0xc0, v1
	s_addc_u32 s25, s7, 0
	s_ashr_i32 s8, s12, 6
	v_and_or_b32 v3, v2, s6, v3
	v_and_b32_e32 v4, 4, v4
	v_and_b32_e32 v5, 24, v5
	v_sub_u32_e32 v0, v0, v1
	s_ashr_i32 s13, s12, 8
	s_lshl_b32 s30, s8, 10
	v_or3_b32 v3, v3, v4, v5
	v_lshlrev_b32_e32 v4, 5, v13
	v_ashrrev_i16_sdwa v0, v206, sext(v0) dst_sel:DWORD dst_unused:UNUSED_PAD src0_sel:DWORD src1_sel:BYTE_0
	v_readlane_b32 s6, v255, 11
	v_and_b32_e32 v4, 32, v4
	v_bfe_i32 v14, v0, 0, 16
	v_readlane_b32 s7, v255, 12
	s_add_u32 s58, s24, s6
	v_add_lshl_u32 v0, v4, v14, 1
	s_addc_u32 s59, s25, s7
	s_add_i32 s31, s30, 0
	v_lshl_add_u32 v184, v3, 12, v0
	s_add_i32 m0, s31, 0x10000
	v_lshl_add_u32 v132, v2, 12, v0
	v_lshrrev_b32_e32 v238, 6, v203
	v_and_b32_e32 v239, 63, v203
	v_lshrrev_b32_e32 v240, 3, v239
	v_and_b32_e32 v241, 7, v239
	v_and_b32_e32 v246, 1, v238
	v_lshlrev_b32_e32 v246, 2, v246
	v_lshrrev_b32_e32 v247, 1, v240
	v_or_b32_e32 v246, v246, v247
	v_xor_b32_e32 v241, v241, v246
	v_lshlrev_b32_e32 v241, 4, v241
	v_lshl_add_u32 v247, v238, 3, v240
	v_lshl_add_u32 v132, v247, 12, v241
	v_add_u32_e32 v130, 0x40000, v132
	v_and_b32_e32 v248, 3, v247
	v_lshlrev_b32_e32 v249, 1, v247
	v_and_b32_e32 v249, 24, v249
	v_lshrrev_b32_e32 v250, 2, v247
	v_and_b32_e32 v250, 4, v250
	v_and_b32_e32 v251, 32, v247
	v_or3_b32 v248, v248, v249, v250
	v_or_b32_e32 v248, v248, v251
	v_lshl_add_u32 v184, v248, 12, v241
	v_add_u32_e32 v128, 0x40000, v184
	global_load_lds_dwordx4 v184, s[58:59]
	s_add_i32 m0, s31, 0x12000
	s_add_u32 s6, s58, 0x80000
	global_load_lds_dwordx4 v128, s[58:59]
	s_addc_u32 s7, s59, 0
	s_add_i32 m0, s31, 0x14000
	v_mov_b32_e32 v129, v185
	global_load_lds_dwordx4 v184, s[6:7]
	s_add_i32 m0, s31, 0x16000
	v_mov_b32_e32 v133, v185
	global_load_lds_dwordx4 v128, s[6:7]
	v_readlane_b32 s6, v255, 9
	v_readlane_b32 s7, v255, 10
	s_add_u32 s56, s9, s6
	s_addc_u32 s57, s11, s7
	s_add_i32 s34, s31, 0x2000
	s_mov_b32 m0, s31
	s_add_u32 s6, s56, 0x80000
	global_load_lds_dwordx4 v132, s[56:57]
	s_mov_b32 m0, s34
	s_addc_u32 s7, s57, 0
	s_add_i32 s35, s31, 0x4000
	global_load_lds_dwordx4 v130, s[56:57]
	s_mov_b32 m0, s35
	s_add_i32 s36, s31, 0x6000
	global_load_lds_dwordx4 v132, s[6:7]
	s_mov_b32 m0, s36
	v_mov_b32_e32 v131, v185
	global_load_lds_dwordx4 v130, s[6:7]
	s_cmp_eq_u32 s13, 1
	s_mov_b32 s79, s50
	v_lshl_add_u64 v[6:7], s[58:59], 0, v[184:185]
	v_lshl_add_u64 v[4:5], s[58:59], 0, v[128:129]
	v_lshl_add_u64 v[0:1], s[56:57], 0, v[132:133]
	s_cselect_b64 s[6:7], -1, 0
	s_cmp_lg_u32 s13, 1
	v_lshl_add_u64 v[2:3], s[56:57], 0, v[130:131]
	s_cbranch_scc1 .LBB0_18
	s_barrier
.LBB0_18:
	s_add_u32 s14, s74, 0x23400000
	s_addc_u32 s15, s75, 0
	s_lshl_b32 s8, s8, 5
	s_and_b32 s8, s8, 0x60
	s_add_i32 m0, s31, 0x18000
	v_lshl_add_u64 v[6:7], v[6:7], 0, s[26:27]
	s_lshl_b32 s37, s13, 6
	s_lshl_b32 s13, s13, 13
	s_lshl_b32 s33, s8, 7
	s_waitcnt vmcnt(2)
	s_barrier
	global_load_lds_dwordx4 v[6:7], off
	v_lshl_add_u64 v[4:5], v[4:5], 0, s[26:27]
	s_add_i32 m0, s31, 0x1a000
	s_add_i32 s38, s31, 0x8000
	s_add_i32 s39, s31, 0xa000
	global_load_lds_dwordx4 v[4:5], off
	v_lshl_add_u64 v[0:1], v[0:1], 0, s[26:27]
	s_mov_b32 m0, s38
	s_add_u32 s20, s58, 0x80080
	global_load_lds_dwordx4 v[0:1], off
	v_lshl_add_u64 v[0:1], v[2:3], 0, s[26:27]
	s_mov_b32 m0, s39
	s_addc_u32 s21, s59, 0
	global_load_lds_dwordx4 v[0:1], off
	s_add_i32 m0, s31, 0x1c000
	v_lshl_add_u64 v[0:1], s[20:21], 0, v[184:185]
	global_load_lds_dwordx4 v[0:1], off
	v_lshl_add_u64 v[0:1], s[20:21], 0, v[128:129]
	s_add_i32 m0, s31, 0x1e000
	v_and_b32_e32 v140, 15, v8
	global_load_lds_dwordx4 v[0:1], off
	v_lshrrev_b32_e32 v0, 1, v8
	v_and_b32_e32 v0, 24, v0
	v_lshlrev_b32_e32 v1, 1, v0
	v_lshlrev_b32_e32 v2, 2, v8
	v_or_b32_e32 v142, s8, v0
	v_lshlrev_b32_e32 v0, 15, v13
	v_lshl_or_b32 v1, v140, 6, v1
	v_and_b32_e32 v2, 32, v2
	v_and_b32_e32 v0, 0xffff0000, v0
	v_bitop3_b32 v3, v1, s13, v2 bitop3:0xde
	v_bitop3_b32 v141, v1, s33, v2 bitop3:0xde
	v_lshl_add_u32 v0, v12, 12, v0
	v_and_b32_e32 v1, 1, v13
	v_lshl_or_b32 v0, v1, 6, v0
	v_lshl_add_u32 v134, v14, 1, v0
	v_lshlrev_b32_e32 v0, 15, v9
	v_and_b32_e32 v0, 0xffff0000, v0
	s_waitcnt vmcnt(6)
	v_lshl_add_u32 v0, v10, 12, v0
	v_and_b32_e32 v1, 1, v9
	s_cmpk_lt_u32 s12, 0x100
	v_lshl_or_b32 v0, v1, 6, v0
	v_readlane_b32 s12, v255, 7
	s_cselect_b64 s[42:43], -1, 0
	v_mov_b32_e32 v135, v185
	v_lshl_add_u32 v136, v11, 1, v0
	v_mov_b32_e32 v137, v185
	s_mov_b32 s48, 0
	v_add_u32_e32 v143, 0, v3
	v_readlane_b32 s49, v255, 6
	s_mov_b32 s50, s12
	s_barrier
	v_readlane_b32 s13, v255, 8
	v_and_b32_e32 v246, 15, v203
	v_bfe_u32 v247, v203, 4, 2
	v_lshrrev_b32_e32 v248, 1, v246
	v_xor_b32_e32 v249, v247, v248
	v_lshlrev_b32_e32 v249, 4, v249
	v_lshrrev_b32_e32 v250, 3, v246
	v_lshlrev_b32_e32 v250, 10, v250
	v_and_b32_e32 v251, 7, v246
	v_lshl_add_u32 v250, v251, 7, v250
	v_add_u32_e32 v250, v250, v249
	v_lshrrev_b32_e32 v251, 8, v203
	v_lshl_add_u32 v143, v251, 13, v250
	v_xor_b32_e32 v240, 64, v143
	v_bfe_u32 v251, v203, 6, 2
	v_lshl_add_u32 v141, v251, 12, v250
	v_xor_b32_e32 v241, 64, v141
	v_mov_b32_e32 v134, v132
	v_mov_b32_e32 v136, v130
	s_branch .LBB0_21

.LBB0_28:
	s_add_u32 s8, s56, 0xfff80080
	s_addc_u32 s12, s57, -1
	s_add_i32 s20, 0, 0x10000
	s_cmp_eq_u32 s63, 28
	s_cselect_b32 s13, s47, s12
	s_cselect_b32 s12, s51, s8
	v_add_u32_e32 v138, s20, v141
	v_add_u32_e32 v238, s20, v241
	s_cselect_b32 s59, s45, s62
	s_cselect_b32 s58, s60, s61
	s_add_i32 s8, 0, 0x14000
	ds_read_b128 v[144:147], v138
	ds_read_b128 v[148:151], v238
	ds_read_b128 v[152:155], v138 offset:2048
	ds_read_b128 v[156:159], v238 offset:2048
	v_add_u32_e32 v138, s8, v141
	v_add_u32_e32 v238, s8, v241
	ds_read_b128 v[160:163], v138
	ds_read_b128 v[164:167], v238
	ds_read_b128 v[168:171], v138 offset:2048
	ds_read_b128 v[172:175], v238 offset:2048
	v_lshl_add_u64 v[138:139], s[56:57], 0, v[134:135]
	s_add_i32 m0, s31, 0xc000
	ds_read_b128 v[176:179], v143
	ds_read_b128 v[180:183], v240
	ds_read_b128 v[186:189], v143 offset:2048
	ds_read_b128 v[192:195], v240 offset:2048
	ds_read_b128 v[196:199], v143 offset:4096
	ds_read_b128 v[214:217], v240 offset:4096
	ds_read_b128 v[218:221], v143 offset:6144
	ds_read_b128 v[222:225], v240 offset:6144
	global_load_lds_dwordx4 v[138:139], off
	v_lshl_add_u64 v[138:139], s[56:57], 0, v[136:137]
	s_add_i32 m0, s31, 0xe000
	s_nop 0
	global_load_lds_dwordx4 v[138:139], off
	s_waitcnt vmcnt(8)
	s_waitcnt lgkmcnt(0)
	s_barrier
	s_setprio 1
	s_waitcnt lgkmcnt(0)
	v_mfma_f32_16x16x32_bf16 v[124:127], v[144:147], v[176:179], v[124:127]
	v_mfma_f32_16x16x32_bf16 v[120:123], v[152:155], v[176:179], v[120:123]
	v_mfma_f32_16x16x32_bf16 v[116:119], v[144:147], v[186:189], v[116:119]
	v_mfma_f32_16x16x32_bf16 v[108:111], v[152:155], v[186:189], v[108:111]
	v_mfma_f32_16x16x32_bf16 v[100:103], v[144:147], v[196:199], v[100:103]
	v_mfma_f32_16x16x32_bf16 v[92:95], v[152:155], v[196:199], v[92:95]
	v_mfma_f32_16x16x32_bf16 v[84:87], v[144:147], v[218:221], v[84:87]
	v_mfma_f32_16x16x32_bf16 v[76:79], v[152:155], v[218:221], v[76:79]
	v_mfma_f32_16x16x32_bf16 v[124:127], v[148:151], v[180:183], v[124:127]
	v_mfma_f32_16x16x32_bf16 v[120:123], v[156:159], v[180:183], v[120:123]
	v_mfma_f32_16x16x32_bf16 v[116:119], v[148:151], v[192:195], v[116:119]
	v_mfma_f32_16x16x32_bf16 v[108:111], v[156:159], v[192:195], v[108:111]
	v_mfma_f32_16x16x32_bf16 v[100:103], v[148:151], v[214:217], v[100:103]
	v_mfma_f32_16x16x32_bf16 v[92:95], v[156:159], v[214:217], v[92:95]
	v_mfma_f32_16x16x32_bf16 v[84:87], v[148:151], v[222:225], v[84:87]
	v_mfma_f32_16x16x32_bf16 v[76:79], v[156:159], v[222:225], v[76:79]
	s_setprio 0
	s_setprio 1
	v_mfma_f32_16x16x32_bf16 v[112:115], v[160:163], v[176:179], v[112:115]
	v_mfma_f32_16x16x32_bf16 v[104:107], v[168:171], v[176:179], v[104:107]
	v_mfma_f32_16x16x32_bf16 v[96:99], v[160:163], v[186:189], v[96:99]
	v_mfma_f32_16x16x32_bf16 v[88:91], v[168:171], v[186:189], v[88:91]
	v_mfma_f32_16x16x32_bf16 v[80:83], v[160:163], v[196:199], v[80:83]
	v_mfma_f32_16x16x32_bf16 v[72:75], v[168:171], v[196:199], v[72:75]
	v_mfma_f32_16x16x32_bf16 v[68:71], v[160:163], v[218:221], v[68:71]
	v_mfma_f32_16x16x32_bf16 v[64:67], v[168:171], v[218:221], v[64:67]
	v_mfma_f32_16x16x32_bf16 v[112:115], v[164:167], v[180:183], v[112:115]
	v_mfma_f32_16x16x32_bf16 v[104:107], v[172:175], v[180:183], v[104:107]
	v_mfma_f32_16x16x32_bf16 v[96:99], v[164:167], v[192:195], v[96:99]
	v_mfma_f32_16x16x32_bf16 v[88:91], v[172:175], v[192:195], v[88:91]
	v_mfma_f32_16x16x32_bf16 v[80:83], v[164:167], v[214:217], v[80:83]
	v_mfma_f32_16x16x32_bf16 v[72:75], v[172:175], v[214:217], v[72:75]
	v_mfma_f32_16x16x32_bf16 v[68:71], v[164:167], v[222:225], v[68:71]
	v_mfma_f32_16x16x32_bf16 v[64:67], v[172:175], v[222:225], v[64:67]
	s_setprio 0
	s_barrier
	s_add_i32 s20, s20, s30
	v_lshl_add_u64 v[138:139], s[58:59], 0, v[184:185]
	s_mov_b32 m0, s20
	ds_read_b128 v[176:179], v143 offset:16384
	ds_read_b128 v[180:183], v240 offset:16384
	ds_read_b128 v[186:189], v143 offset:18432
	ds_read_b128 v[192:195], v240 offset:18432
	ds_read_b128 v[196:199], v143 offset:20480
	ds_read_b128 v[214:217], v240 offset:20480
	ds_read_b128 v[218:221], v143 offset:22528
	ds_read_b128 v[222:225], v240 offset:22528
	global_load_lds_dwordx4 v[138:139], off
	s_add_i32 m0, s20, 0x2000
	s_add_u32 s20, s58, 0x80000
	v_lshl_add_u64 v[200:201], s[58:59], 0, v[128:129]
	s_addc_u32 s21, s59, 0
	s_add_i32 s8, s8, s30
	global_load_lds_dwordx4 v[200:201], off
	v_lshl_add_u64 v[226:227], s[20:21], 0, v[184:185]
	s_mov_b32 m0, s8
	v_lshl_add_u64 v[228:229], s[12:13], 0, v[130:131]
	global_load_lds_dwordx4 v[226:227], off
	v_lshl_add_u64 v[226:227], s[20:21], 0, v[128:129]
	s_add_i32 m0, s8, 0x2000
	s_nop 0
	global_load_lds_dwordx4 v[226:227], off
	v_lshl_add_u64 v[226:227], s[12:13], 0, v[132:133]
	s_mov_b32 m0, s31
	s_nop 0
	global_load_lds_dwordx4 v[226:227], off
	s_mov_b32 m0, s34
	s_nop 0
	global_load_lds_dwordx4 v[228:229], off
	s_waitcnt vmcnt(8)
	s_waitcnt lgkmcnt(0)
	s_barrier
	s_setprio 1
	s_waitcnt lgkmcnt(0)
	v_mfma_f32_16x16x32_bf16 v[60:63], v[144:147], v[176:179], v[60:63]
	v_mfma_f32_16x16x32_bf16 v[56:59], v[152:155], v[176:179], v[56:59]
	v_mfma_f32_16x16x32_bf16 v[52:55], v[144:147], v[186:189], v[52:55]
	v_mfma_f32_16x16x32_bf16 v[44:47], v[152:155], v[186:189], v[44:47]
	v_mfma_f32_16x16x32_bf16 v[36:39], v[144:147], v[196:199], v[36:39]
	v_mfma_f32_16x16x32_bf16 v[28:31], v[152:155], v[196:199], v[28:31]
	v_mfma_f32_16x16x32_bf16 v[20:23], v[144:147], v[218:221], v[20:23]
	v_mfma_f32_16x16x32_bf16 v[12:15], v[152:155], v[218:221], v[12:15]
	v_mfma_f32_16x16x32_bf16 v[60:63], v[148:151], v[180:183], v[60:63]
	v_mfma_f32_16x16x32_bf16 v[56:59], v[156:159], v[180:183], v[56:59]
	v_mfma_f32_16x16x32_bf16 v[52:55], v[148:151], v[192:195], v[52:55]
	v_mfma_f32_16x16x32_bf16 v[44:47], v[156:159], v[192:195], v[44:47]
	v_mfma_f32_16x16x32_bf16 v[36:39], v[148:151], v[214:217], v[36:39]
	v_mfma_f32_16x16x32_bf16 v[28:31], v[156:159], v[214:217], v[28:31]
	v_mfma_f32_16x16x32_bf16 v[20:23], v[148:151], v[222:225], v[20:23]
	v_mfma_f32_16x16x32_bf16 v[12:15], v[156:159], v[222:225], v[12:15]
	s_setprio 0
	s_setprio 1
	v_mfma_f32_16x16x32_bf16 v[48:51], v[160:163], v[176:179], v[48:51]
	v_mfma_f32_16x16x32_bf16 v[40:43], v[168:171], v[176:179], v[40:43]
	v_mfma_f32_16x16x32_bf16 v[32:35], v[160:163], v[186:189], v[32:35]
	v_mfma_f32_16x16x32_bf16 v[24:27], v[168:171], v[186:189], v[24:27]
	v_mfma_f32_16x16x32_bf16 v[16:19], v[160:163], v[196:199], v[16:19]
	v_mfma_f32_16x16x32_bf16 v[8:11], v[168:171], v[196:199], v[8:11]
	v_mfma_f32_16x16x32_bf16 v[4:7], v[160:163], v[218:221], v[4:7]
	v_mfma_f32_16x16x32_bf16 v[0:3], v[168:171], v[218:221], v[0:3]
	v_mfma_f32_16x16x32_bf16 v[48:51], v[164:167], v[180:183], v[48:51]
	v_mfma_f32_16x16x32_bf16 v[40:43], v[172:175], v[180:183], v[40:43]
	v_mfma_f32_16x16x32_bf16 v[32:35], v[164:167], v[192:195], v[32:35]
	v_mfma_f32_16x16x32_bf16 v[24:27], v[172:175], v[192:195], v[24:27]
	v_mfma_f32_16x16x32_bf16 v[16:19], v[164:167], v[214:217], v[16:19]
	v_mfma_f32_16x16x32_bf16 v[8:11], v[172:175], v[214:217], v[8:11]
	v_mfma_f32_16x16x32_bf16 v[4:7], v[164:167], v[222:225], v[4:7]
	v_mfma_f32_16x16x32_bf16 v[0:3], v[172:175], v[222:225], v[0:3]
	s_setprio 0
	s_barrier
	s_add_i32 s8, 0, 0x18000
	s_add_i32 s20, 0, 0x1c000
	v_add_u32_e32 v156, s8, v141
	v_add_u32_e32 v238, s8, v241
	v_add_u32_e32 v172, s20, v141
	v_add_u32_e32 v239, s20, v241
	ds_read_b128 v[144:147], v156
	ds_read_b128 v[148:151], v238
	ds_read_b128 v[152:155], v156 offset:2048
	ds_read_b128 v[156:159], v238 offset:2048
	ds_read_b128 v[160:163], v172
	ds_read_b128 v[164:167], v239
	ds_read_b128 v[168:171], v172 offset:2048
	ds_read_b128 v[172:175], v239 offset:2048
	s_add_u32 s12, s12, 0x80000
	s_addc_u32 s13, s13, 0
	s_mov_b32 m0, s35
	v_lshl_add_u64 v[230:231], s[12:13], 0, v[132:133]
	ds_read_b128 v[176:179], v143 offset:32768
	ds_read_b128 v[180:183], v240 offset:32768
	ds_read_b128 v[186:189], v143 offset:34816
	ds_read_b128 v[192:195], v240 offset:34816
	ds_read_b128 v[196:199], v143 offset:36864
	ds_read_b128 v[214:217], v240 offset:36864
	ds_read_b128 v[218:221], v143 offset:38912
	ds_read_b128 v[222:225], v240 offset:38912
	global_load_lds_dwordx4 v[230:231], off
	v_lshl_add_u64 v[230:231], s[12:13], 0, v[130:131]
	s_mov_b32 m0, s36
	s_nop 0
	global_load_lds_dwordx4 v[230:231], off
	s_waitcnt vmcnt(8)
	s_waitcnt lgkmcnt(0)
	s_barrier
	s_setprio 1
	s_waitcnt lgkmcnt(0)
	v_mfma_f32_16x16x32_bf16 v[124:127], v[144:147], v[176:179], v[124:127]
	v_mfma_f32_16x16x32_bf16 v[120:123], v[152:155], v[176:179], v[120:123]
	v_mfma_f32_16x16x32_bf16 v[116:119], v[144:147], v[186:189], v[116:119]
	v_mfma_f32_16x16x32_bf16 v[108:111], v[152:155], v[186:189], v[108:111]
	v_mfma_f32_16x16x32_bf16 v[100:103], v[144:147], v[196:199], v[100:103]
	v_mfma_f32_16x16x32_bf16 v[92:95], v[152:155], v[196:199], v[92:95]
	v_mfma_f32_16x16x32_bf16 v[84:87], v[144:147], v[218:221], v[84:87]
	v_mfma_f32_16x16x32_bf16 v[76:79], v[152:155], v[218:221], v[76:79]
	v_mfma_f32_16x16x32_bf16 v[124:127], v[148:151], v[180:183], v[124:127]
	v_mfma_f32_16x16x32_bf16 v[120:123], v[156:159], v[180:183], v[120:123]
	v_mfma_f32_16x16x32_bf16 v[116:119], v[148:151], v[192:195], v[116:119]
	v_mfma_f32_16x16x32_bf16 v[108:111], v[156:159], v[192:195], v[108:111]
	v_mfma_f32_16x16x32_bf16 v[100:103], v[148:151], v[214:217], v[100:103]
	v_mfma_f32_16x16x32_bf16 v[92:95], v[156:159], v[214:217], v[92:95]
	v_mfma_f32_16x16x32_bf16 v[84:87], v[148:151], v[222:225], v[84:87]
	v_mfma_f32_16x16x32_bf16 v[76:79], v[156:159], v[222:225], v[76:79]
	s_setprio 0
	s_setprio 1
	v_mfma_f32_16x16x32_bf16 v[112:115], v[160:163], v[176:179], v[112:115]
	v_mfma_f32_16x16x32_bf16 v[104:107], v[168:171], v[176:179], v[104:107]
	v_mfma_f32_16x16x32_bf16 v[96:99], v[160:163], v[186:189], v[96:99]
	v_mfma_f32_16x16x32_bf16 v[88:91], v[168:171], v[186:189], v[88:91]
	v_mfma_f32_16x16x32_bf16 v[80:83], v[160:163], v[196:199], v[80:83]
	v_mfma_f32_16x16x32_bf16 v[72:75], v[168:171], v[196:199], v[72:75]
	v_mfma_f32_16x16x32_bf16 v[68:71], v[160:163], v[218:221], v[68:71]
	v_mfma_f32_16x16x32_bf16 v[64:67], v[168:171], v[218:221], v[64:67]
	v_mfma_f32_16x16x32_bf16 v[112:115], v[164:167], v[180:183], v[112:115]
	v_mfma_f32_16x16x32_bf16 v[104:107], v[172:175], v[180:183], v[104:107]
	v_mfma_f32_16x16x32_bf16 v[96:99], v[164:167], v[192:195], v[96:99]
	v_mfma_f32_16x16x32_bf16 v[88:91], v[172:175], v[192:195], v[88:91]
	v_mfma_f32_16x16x32_bf16 v[80:83], v[164:167], v[214:217], v[80:83]
	v_mfma_f32_16x16x32_bf16 v[72:75], v[172:175], v[214:217], v[72:75]
	v_mfma_f32_16x16x32_bf16 v[68:71], v[164:167], v[222:225], v[68:71]
	v_mfma_f32_16x16x32_bf16 v[64:67], v[172:175], v[222:225], v[64:67]
	s_setprio 0
	s_barrier
	s_add_i32 s8, s8, s30
	v_lshl_add_u64 v[138:139], v[138:139], 0, s[26:27]
	s_mov_b32 m0, s8
	ds_read_b128 v[176:179], v143 offset:49152
	ds_read_b128 v[180:183], v240 offset:49152
	ds_read_b128 v[186:189], v143 offset:51200
	ds_read_b128 v[192:195], v240 offset:51200
	ds_read_b128 v[196:199], v143 offset:53248
	ds_read_b128 v[214:217], v240 offset:53248
	ds_read_b128 v[218:221], v143 offset:55296
	ds_read_b128 v[222:225], v240 offset:55296
	global_load_lds_dwordx4 v[138:139], off
	s_add_i32 m0, s8, 0x2000
	s_add_u32 s12, s58, 0x80080
	v_lshl_add_u64 v[138:139], v[200:201], 0, s[26:27]
	s_addc_u32 s13, s59, 0
	s_add_i32 s8, s20, s30
	global_load_lds_dwordx4 v[138:139], off
	v_lshl_add_u64 v[138:139], s[12:13], 0, v[184:185]
	s_mov_b32 m0, s8
	s_nop 0
	global_load_lds_dwordx4 v[138:139], off
	v_lshl_add_u64 v[138:139], s[12:13], 0, v[128:129]
	s_add_i32 m0, s8, 0x2000
	s_nop 0
	global_load_lds_dwordx4 v[138:139], off
	v_lshl_add_u64 v[138:139], v[226:227], 0, s[26:27]
	s_mov_b32 m0, s38
	s_nop 0
	global_load_lds_dwordx4 v[138:139], off
	v_lshl_add_u64 v[138:139], v[228:229], 0, s[26:27]
	s_mov_b32 m0, s39
	s_nop 0
	global_load_lds_dwordx4 v[138:139], off
	s_waitcnt vmcnt(8)
	s_waitcnt lgkmcnt(0)
	s_barrier
	s_setprio 1
	s_waitcnt lgkmcnt(0)
	v_mfma_f32_16x16x32_bf16 v[60:63], v[144:147], v[176:179], v[60:63]
	v_mfma_f32_16x16x32_bf16 v[56:59], v[152:155], v[176:179], v[56:59]
	v_mfma_f32_16x16x32_bf16 v[52:55], v[144:147], v[186:189], v[52:55]
	v_mfma_f32_16x16x32_bf16 v[44:47], v[152:155], v[186:189], v[44:47]
	v_mfma_f32_16x16x32_bf16 v[36:39], v[144:147], v[196:199], v[36:39]
	v_mfma_f32_16x16x32_bf16 v[28:31], v[152:155], v[196:199], v[28:31]
	v_mfma_f32_16x16x32_bf16 v[20:23], v[144:147], v[218:221], v[20:23]
	v_mfma_f32_16x16x32_bf16 v[12:15], v[152:155], v[218:221], v[12:15]
	v_mfma_f32_16x16x32_bf16 v[60:63], v[148:151], v[180:183], v[60:63]
	v_mfma_f32_16x16x32_bf16 v[56:59], v[156:159], v[180:183], v[56:59]
	v_mfma_f32_16x16x32_bf16 v[52:55], v[148:151], v[192:195], v[52:55]
	v_mfma_f32_16x16x32_bf16 v[44:47], v[156:159], v[192:195], v[44:47]
	v_mfma_f32_16x16x32_bf16 v[36:39], v[148:151], v[214:217], v[36:39]
	v_mfma_f32_16x16x32_bf16 v[28:31], v[156:159], v[214:217], v[28:31]
	v_mfma_f32_16x16x32_bf16 v[20:23], v[148:151], v[222:225], v[20:23]
	v_mfma_f32_16x16x32_bf16 v[12:15], v[156:159], v[222:225], v[12:15]
	s_setprio 0
	s_setprio 1
	v_mfma_f32_16x16x32_bf16 v[48:51], v[160:163], v[176:179], v[48:51]
	v_mfma_f32_16x16x32_bf16 v[40:43], v[168:171], v[176:179], v[40:43]
	v_mfma_f32_16x16x32_bf16 v[32:35], v[160:163], v[186:189], v[32:35]
	v_mfma_f32_16x16x32_bf16 v[24:27], v[168:171], v[186:189], v[24:27]
	v_mfma_f32_16x16x32_bf16 v[16:19], v[160:163], v[196:199], v[16:19]
	v_mfma_f32_16x16x32_bf16 v[8:11], v[168:171], v[196:199], v[8:11]
	v_mfma_f32_16x16x32_bf16 v[4:7], v[160:163], v[218:221], v[4:7]
	v_mfma_f32_16x16x32_bf16 v[0:3], v[168:171], v[218:221], v[0:3]
	v_mfma_f32_16x16x32_bf16 v[48:51], v[164:167], v[180:183], v[48:51]
	v_mfma_f32_16x16x32_bf16 v[40:43], v[172:175], v[180:183], v[40:43]
	v_mfma_f32_16x16x32_bf16 v[32:35], v[164:167], v[192:195], v[32:35]
	v_mfma_f32_16x16x32_bf16 v[24:27], v[172:175], v[192:195], v[24:27]
	v_mfma_f32_16x16x32_bf16 v[16:19], v[164:167], v[214:217], v[16:19]
	v_mfma_f32_16x16x32_bf16 v[8:11], v[172:175], v[214:217], v[8:11]
	v_mfma_f32_16x16x32_bf16 v[4:7], v[164:167], v[222:225], v[4:7]
	v_mfma_f32_16x16x32_bf16 v[0:3], v[172:175], v[222:225], v[0:3]
	s_setprio 0
	s_barrier
	s_add_i32 s63, s63, 2
	s_add_u32 s56, s56, 0x100
	s_addc_u32 s57, s57, 0
	s_add_u32 s61, s61, 0x100
	s_addc_u32 s62, s62, 0
	s_cmp_gt_u32 s63, 29
	s_cbranch_scc0 .LBB0_28
	s_and_b64 vcc, exec, s[42:43]
	s_cbranch_vccz .LBB0_31
	s_barrier

.LBB0_173:
	v_readlane_b32 s6, v254, 18
	v_mov_b32_e32 v8, v203
	v_readlane_b32 s7, v254, 19
	s_andn2_b64 vcc, exec, s[6:7]
	v_readfirstlane_b32 s6, v8
	s_cbranch_vccnz .LBB0_317
	v_lshlrev_b32_e32 v0, 4, v8
	v_add_u32_e32 v1, 0x2000, v0
	v_ashrrev_i32_e32 v2, 31, v1
	v_lshrrev_b32_e32 v2, 22, v2
	v_add_u32_e32 v2, v1, v2
	v_ashrrev_i32_e32 v9, 10, v2
	v_mul_i32_i24_e32 v2, 0x400, v9
	v_sub_u32_e32 v1, v1, v2
	v_lshrrev_b32_e32 v2, 4, v1
	v_bitop3_b32 v1, v2, v1, 32 bitop3:0x6c
	v_ashrrev_i32_e32 v2, 31, v1
	v_lshrrev_b32_e32 v2, 26, v2
	v_add_u32_e32 v2, v1, v2
	v_lshlrev_b32_e32 v3, 3, v9
	v_ashrrev_i32_e32 v10, 6, v2
	v_and_b32_e32 v3, -16, v3
	v_add_u32_e32 v3, v10, v3
	v_and_b32_e32 v4, 3, v10
	s_mov_b32 s9, 0xfffe0
	v_lshrrev_b32_e32 v5, 2, v3
	v_lshlrev_b32_e32 v6, 1, v3
	v_and_b32_e32 v2, 0xc0, v2
	v_and_or_b32 v4, v3, s9, v4
	v_and_b32_e32 v5, 4, v5
	v_and_b32_e32 v6, 24, v6
	v_sub_u32_e32 v1, v1, v2
	v_or3_b32 v4, v4, v5, v6
	v_lshlrev_b32_e32 v5, 5, v9
	v_ashrrev_i16_sdwa v1, v206, sext(v1) dst_sel:DWORD dst_unused:UNUSED_PAD src0_sel:DWORD src1_sel:BYTE_0
	v_and_b32_e32 v5, 32, v5
	v_bfe_i32 v11, v1, 0, 16
	v_add_lshl_u32 v1, v5, v11, 1
	v_lshl_add_u32 v128, v4, 12, v1
	v_lshl_add_u32 v130, v3, 12, v1
	v_bfe_i32 v1, v8, 27, 1
	v_lshrrev_b32_e32 v1, 22, v1
	v_add_u32_e32 v1, v0, v1
	v_and_b32_e32 v1, 0xfffffc00, v1
	v_sub_u32_e32 v0, v0, v1
	v_lshrrev_b32_e32 v1, 4, v0
	v_ashrrev_i32_e32 v2, 31, v8
	v_bitop3_b32 v0, v1, v0, 32 bitop3:0x6c
	v_lshrrev_b32_e32 v2, 26, v2
	v_ashrrev_i32_e32 v1, 31, v0
	v_add_u32_e32 v2, v8, v2
	s_waitcnt lgkmcnt(0)
	s_add_u32 s77, s74, 0xb400000
	v_lshrrev_b32_e32 v1, 26, v1
	v_ashrrev_i32_e32 v13, 6, v2
	s_addc_u32 s79, s75, 0
	s_mul_i32 s8, s16, 0x1400000
	v_add_u32_e32 v1, v0, v1
	v_lshlrev_b32_e32 v2, 3, v13
	s_mul_hi_u32 s7, s16, 0x1400000
	s_add_u32 s8, s74, s8
	v_ashrrev_i32_e32 v12, 6, v1
	v_and_b32_e32 v2, -16, v2
	s_addc_u32 s7, s75, s7
	v_add_u32_e32 v2, v12, v2
	s_add_u32 s11, s8, 0x200000
	v_and_b32_e32 v3, 3, v12
	v_lshrrev_b32_e32 v4, 2, v2
	v_lshlrev_b32_e32 v5, 1, v2
	v_and_b32_e32 v1, 0xc0, v1
	s_addc_u32 s24, s7, 0
	s_ashr_i32 s8, s6, 6
	v_and_or_b32 v3, v2, s9, v3
	v_and_b32_e32 v4, 4, v4
	v_and_b32_e32 v5, 24, v5
	v_sub_u32_e32 v0, v0, v1
	s_ashr_i32 s7, s6, 8
	s_lshl_b32 s25, s8, 10
	v_or3_b32 v3, v3, v4, v5
	v_lshlrev_b32_e32 v4, 5, v13
	v_ashrrev_i16_sdwa v0, v206, sext(v0) dst_sel:DWORD dst_unused:UNUSED_PAD src0_sel:DWORD src1_sel:BYTE_0
	v_readlane_b32 s12, v255, 27
	v_and_b32_e32 v4, 32, v4
	v_bfe_i32 v14, v0, 0, 16
	v_readlane_b32 s13, v255, 28
	s_add_u32 s44, s11, s12
	v_add_lshl_u32 v0, v4, v14, 1
	s_addc_u32 s45, s24, s13
	s_add_i32 s30, s25, 0
	v_lshl_add_u32 v184, v3, 12, v0
	s_add_i32 m0, s30, 0x10000
	v_lshl_add_u32 v132, v2, 12, v0
	v_lshrrev_b32_e32 v238, 6, v203
	v_and_b32_e32 v239, 63, v203
	v_lshrrev_b32_e32 v240, 3, v239
	v_and_b32_e32 v241, 7, v239
	v_and_b32_e32 v246, 1, v238
	v_lshlrev_b32_e32 v246, 2, v246
	v_lshrrev_b32_e32 v247, 1, v240
	v_or_b32_e32 v246, v246, v247
	v_xor_b32_e32 v241, v241, v246
	v_lshlrev_b32_e32 v241, 4, v241
	v_lshl_add_u32 v247, v238, 3, v240
	v_lshl_add_u32 v132, v247, 12, v241
	v_add_u32_e32 v130, 0x40000, v132
	v_and_b32_e32 v248, 3, v247
	v_lshlrev_b32_e32 v249, 1, v247
	v_and_b32_e32 v249, 24, v249
	v_lshrrev_b32_e32 v250, 2, v247
	v_and_b32_e32 v250, 4, v250
	v_and_b32_e32 v251, 32, v247
	v_or3_b32 v248, v248, v249, v250
	v_or_b32_e32 v248, v248, v251
	v_lshl_add_u32 v184, v248, 12, v241
	v_add_u32_e32 v128, 0x40000, v184
	global_load_lds_dwordx4 v184, s[44:45]
	s_add_i32 m0, s30, 0x12000
	s_add_u32 s12, s44, 0x80000
	global_load_lds_dwordx4 v128, s[44:45]
	s_addc_u32 s13, s45, 0
	s_add_i32 m0, s30, 0x14000
	v_mov_b32_e32 v129, v185
	global_load_lds_dwordx4 v184, s[12:13]
	s_add_i32 m0, s30, 0x16000
	v_mov_b32_e32 v133, v185
	global_load_lds_dwordx4 v128, s[12:13]
	v_readlane_b32 s12, v255, 42
	v_readlane_b32 s13, v255, 43
	s_add_u32 s14, s77, s12
	s_addc_u32 s15, s79, s13
	s_add_i32 s31, s30, 0x2000
	s_mov_b32 m0, s30
	s_add_u32 s12, s14, 0x80000
	global_load_lds_dwordx4 v132, s[14:15]
	s_mov_b32 m0, s31
	s_addc_u32 s13, s15, 0
	s_add_i32 s38, s30, 0x4000
	global_load_lds_dwordx4 v130, s[14:15]
	s_mov_b32 m0, s38
	s_add_i32 s39, s30, 0x6000
	global_load_lds_dwordx4 v132, s[12:13]
	s_mov_b32 m0, s39
	v_mov_b32_e32 v131, v185
	global_load_lds_dwordx4 v130, s[12:13]
	s_cmp_eq_u32 s7, 1
	v_lshl_add_u64 v[6:7], s[44:45], 0, v[184:185]
	v_lshl_add_u64 v[4:5], s[44:45], 0, v[128:129]
	v_lshl_add_u64 v[0:1], s[14:15], 0, v[132:133]
	s_cselect_b64 s[54:55], -1, 0
	s_cmp_lg_u32 s7, 1
	v_lshl_add_u64 v[2:3], s[14:15], 0, v[130:131]
	s_cbranch_scc1 .LBB0_176
	s_barrier
.LBB0_176:
	s_add_u32 s56, s74, 0x23400000
	s_addc_u32 s57, s75, 0
	s_add_u32 s58, s74, 0xac00000
	s_addc_u32 s59, s75, 0
	s_add_u32 s60, s74, 0xad80000
	s_addc_u32 s61, s75, 0
	s_and_b32 s71, s8, 3
	s_add_i32 m0, s30, 0x18000
	v_lshl_add_u64 v[6:7], v[6:7], 0, s[26:27]
	s_lshl_b32 s96, s7, 6
	s_lshl_b32 s7, s7, 13
	s_lshl_b32 s12, s71, 12
	s_waitcnt vmcnt(2)
	s_barrier
	global_load_lds_dwordx4 v[6:7], off
	v_lshl_add_u64 v[4:5], v[4:5], 0, s[26:27]
	s_add_i32 m0, s30, 0x1a000
	s_add_i32 s34, s30, 0x8000
	s_add_i32 s35, s30, 0xa000
	global_load_lds_dwordx4 v[4:5], off
	v_lshl_add_u64 v[0:1], v[0:1], 0, s[26:27]
	s_mov_b32 m0, s34
	s_add_u32 s8, s44, 0x80080
	global_load_lds_dwordx4 v[0:1], off
	v_lshl_add_u64 v[0:1], v[2:3], 0, s[26:27]
	s_mov_b32 m0, s35
	s_addc_u32 s9, s45, 0
	global_load_lds_dwordx4 v[0:1], off
	s_add_i32 m0, s30, 0x1c000
	v_lshl_add_u64 v[0:1], s[8:9], 0, v[184:185]
	global_load_lds_dwordx4 v[0:1], off
	v_lshl_add_u64 v[0:1], s[8:9], 0, v[128:129]
	s_add_i32 m0, s30, 0x1e000
	v_and_b32_e32 v146, 15, v8
	global_load_lds_dwordx4 v[0:1], off
	v_bfe_u32 v0, v8, 4, 2
	v_lshlrev_b32_e32 v1, 3, v0
	v_lshlrev_b32_e32 v2, 4, v0
	v_cmp_eq_u32_e64 s[40:41], 0, v0
	v_lshlrev_b32_e32 v0, 15, v13
	v_and_b32_e32 v0, 0xffff0000, v0
	v_lshl_or_b32 v148, s71, 5, v1
	v_lshl_add_u32 v0, v12, 12, v0
	v_and_b32_e32 v1, 1, v13
	v_lshl_or_b32 v0, v1, 6, v0
	v_lshl_add_u32 v134, v14, 1, v0
	v_lshlrev_b32_e32 v0, 15, v9
	v_lshlrev_b32_e32 v3, 2, v8
	v_and_b32_e32 v0, 0xffff0000, v0
	v_lshl_or_b32 v2, v146, 6, v2
	v_and_b32_e32 v3, 32, v3
	s_waitcnt vmcnt(6)
	v_lshl_add_u32 v0, v10, 12, v0
	v_and_b32_e32 v1, 1, v9
	v_bitop3_b32 v4, v2, s7, v3 bitop3:0xde
	s_cmpk_lt_u32 s6, 0x100
	v_lshl_or_b32 v0, v1, 6, v0
	v_readlane_b32 s6, v255, 40
	v_bitop3_b32 v147, v2, s12, v3 bitop3:0xde
	s_cselect_b64 s[62:63], -1, 0
	s_mov_b32 s36, 0
	v_mov_b32_e32 v135, v185
	v_lshl_add_u32 v136, v11, 1, v0
	v_mov_b32_e32 v137, v185
	v_add_u32_e32 v149, 0, v4
	v_readlane_b32 s9, v255, 26
	s_mov_b32 s16, s6
	s_barrier
	v_readlane_b32 s7, v255, 41
	v_and_b32_e32 v246, 15, v203
	v_bfe_u32 v247, v203, 4, 2
	v_lshrrev_b32_e32 v248, 1, v246
	v_xor_b32_e32 v249, v247, v248
	v_lshlrev_b32_e32 v249, 4, v249
	v_lshrrev_b32_e32 v250, 3, v246
	v_lshlrev_b32_e32 v250, 10, v250
	v_and_b32_e32 v251, 7, v246
	v_lshl_add_u32 v250, v251, 7, v250
	v_add_u32_e32 v250, v250, v249
	v_lshrrev_b32_e32 v251, 8, v203
	v_lshl_add_u32 v149, v251, 13, v250
	v_xor_b32_e32 v240, 64, v149
	v_bfe_u32 v251, v203, 6, 2
	v_lshl_add_u32 v147, v251, 12, v250
	v_xor_b32_e32 v241, 64, v147
	v_mov_b32_e32 v134, v132
	v_mov_b32_e32 v136, v130
	s_branch .LBB0_179

.LBB0_182:
	s_add_u32 s8, s14, 0xfff80080
	s_addc_u32 s12, s15, -1
	s_add_i32 s20, 0, 0x10000
	s_cmp_eq_u32 s51, 28
	s_cselect_b32 s13, s37, s12
	s_cselect_b32 s12, s46, s8
	s_cselect_b32 s45, s47, s50
	s_cselect_b32 s44, s48, s49
	s_add_i32 s8, 0, 0x14000
	v_add_u32_e32 v154, s20, v147
	v_add_u32_e32 v238, s20, v241
	v_add_u32_e32 v170, s8, v147
	v_add_u32_e32 v239, s8, v241
	ds_read_b128 v[138:141], v154
	ds_read_b128 v[142:145], v238
	ds_read_b128 v[150:153], v154 offset:2048
	ds_read_b128 v[154:157], v238 offset:2048
	ds_read_b128 v[158:161], v170
	ds_read_b128 v[162:165], v239
	ds_read_b128 v[166:169], v170 offset:2048
	ds_read_b128 v[170:173], v239 offset:2048
	v_lshl_add_u64 v[182:183], s[14:15], 0, v[134:135]
	s_add_i32 m0, s30, 0xc000
	ds_read_b128 v[174:177], v149
	ds_read_b128 v[178:181], v240
	ds_read_b128 v[192:195], v149 offset:2048
	ds_read_b128 v[196:199], v240 offset:2048
	ds_read_b128 v[214:217], v149 offset:4096
	ds_read_b128 v[218:221], v240 offset:4096
	ds_read_b128 v[222:225], v149 offset:6144
	ds_read_b128 v[226:229], v240 offset:6144
	global_load_lds_dwordx4 v[182:183], off
	v_lshl_add_u64 v[182:183], s[14:15], 0, v[136:137]
	s_add_i32 m0, s30, 0xe000
	s_nop 0
	global_load_lds_dwordx4 v[182:183], off
	s_waitcnt vmcnt(8)
	s_waitcnt lgkmcnt(0)
	s_barrier
	s_setprio 1
	s_waitcnt lgkmcnt(0)
	v_mfma_f32_16x16x32_bf16 v[124:127], v[138:141], v[174:177], v[124:127]
	v_mfma_f32_16x16x32_bf16 v[120:123], v[150:153], v[174:177], v[120:123]
	v_mfma_f32_16x16x32_bf16 v[108:111], v[138:141], v[192:195], v[108:111]
	v_mfma_f32_16x16x32_bf16 v[104:107], v[150:153], v[192:195], v[104:107]
	v_mfma_f32_16x16x32_bf16 v[92:95], v[138:141], v[214:217], v[92:95]
	v_mfma_f32_16x16x32_bf16 v[88:91], v[150:153], v[214:217], v[88:91]
	v_mfma_f32_16x16x32_bf16 v[76:79], v[138:141], v[222:225], v[76:79]
	v_mfma_f32_16x16x32_bf16 v[72:75], v[150:153], v[222:225], v[72:75]
	v_mfma_f32_16x16x32_bf16 v[124:127], v[142:145], v[178:181], v[124:127]
	v_mfma_f32_16x16x32_bf16 v[120:123], v[154:157], v[178:181], v[120:123]
	v_mfma_f32_16x16x32_bf16 v[108:111], v[142:145], v[196:199], v[108:111]
	v_mfma_f32_16x16x32_bf16 v[104:107], v[154:157], v[196:199], v[104:107]
	v_mfma_f32_16x16x32_bf16 v[92:95], v[142:145], v[218:221], v[92:95]
	v_mfma_f32_16x16x32_bf16 v[88:91], v[154:157], v[218:221], v[88:91]
	v_mfma_f32_16x16x32_bf16 v[76:79], v[142:145], v[226:229], v[76:79]
	v_mfma_f32_16x16x32_bf16 v[72:75], v[154:157], v[226:229], v[72:75]
	s_setprio 0
	s_setprio 1
	v_mfma_f32_16x16x32_bf16 v[116:119], v[158:161], v[174:177], v[116:119]
	v_mfma_f32_16x16x32_bf16 v[112:115], v[166:169], v[174:177], v[112:115]
	v_mfma_f32_16x16x32_bf16 v[100:103], v[158:161], v[192:195], v[100:103]
	v_mfma_f32_16x16x32_bf16 v[96:99], v[166:169], v[192:195], v[96:99]
	v_mfma_f32_16x16x32_bf16 v[84:87], v[158:161], v[214:217], v[84:87]
	v_mfma_f32_16x16x32_bf16 v[80:83], v[166:169], v[214:217], v[80:83]
	v_mfma_f32_16x16x32_bf16 v[68:71], v[158:161], v[222:225], v[68:71]
	v_mfma_f32_16x16x32_bf16 v[64:67], v[166:169], v[222:225], v[64:67]
	v_mfma_f32_16x16x32_bf16 v[116:119], v[162:165], v[178:181], v[116:119]
	v_mfma_f32_16x16x32_bf16 v[112:115], v[170:173], v[178:181], v[112:115]
	v_mfma_f32_16x16x32_bf16 v[100:103], v[162:165], v[196:199], v[100:103]
	v_mfma_f32_16x16x32_bf16 v[96:99], v[170:173], v[196:199], v[96:99]
	v_mfma_f32_16x16x32_bf16 v[84:87], v[162:165], v[218:221], v[84:87]
	v_mfma_f32_16x16x32_bf16 v[80:83], v[170:173], v[218:221], v[80:83]
	v_mfma_f32_16x16x32_bf16 v[68:71], v[162:165], v[226:229], v[68:71]
	v_mfma_f32_16x16x32_bf16 v[64:67], v[170:173], v[226:229], v[64:67]
	s_setprio 0
	s_barrier
	s_add_i32 s20, s20, s25
	v_lshl_add_u64 v[182:183], s[44:45], 0, v[184:185]
	s_mov_b32 m0, s20
	ds_read_b128 v[174:177], v149 offset:16384
	ds_read_b128 v[178:181], v240 offset:16384
	ds_read_b128 v[192:195], v149 offset:18432
	ds_read_b128 v[196:199], v240 offset:18432
	ds_read_b128 v[214:217], v149 offset:20480
	ds_read_b128 v[218:221], v240 offset:20480
	ds_read_b128 v[222:225], v149 offset:22528
	ds_read_b128 v[226:229], v240 offset:22528
	global_load_lds_dwordx4 v[182:183], off
	s_add_i32 m0, s20, 0x2000
	s_add_u32 s20, s44, 0x80000
	v_lshl_add_u64 v[186:187], s[44:45], 0, v[128:129]
	s_addc_u32 s21, s45, 0
	s_add_i32 s8, s8, s25
	global_load_lds_dwordx4 v[186:187], off
	v_lshl_add_u64 v[188:189], s[20:21], 0, v[184:185]
	s_mov_b32 m0, s8
	v_lshl_add_u64 v[200:201], s[12:13], 0, v[130:131]
	global_load_lds_dwordx4 v[188:189], off
	v_lshl_add_u64 v[188:189], s[20:21], 0, v[128:129]
	s_add_i32 m0, s8, 0x2000
	s_nop 0
	global_load_lds_dwordx4 v[188:189], off
	v_lshl_add_u64 v[188:189], s[12:13], 0, v[132:133]
	s_mov_b32 m0, s30
	s_nop 0
	global_load_lds_dwordx4 v[188:189], off
	s_mov_b32 m0, s31
	s_nop 0
	global_load_lds_dwordx4 v[200:201], off
	s_waitcnt vmcnt(8)
	s_waitcnt lgkmcnt(0)
	s_barrier
	s_setprio 1
	s_waitcnt lgkmcnt(0)
	v_mfma_f32_16x16x32_bf16 v[60:63], v[138:141], v[174:177], v[60:63]
	v_mfma_f32_16x16x32_bf16 v[56:59], v[150:153], v[174:177], v[56:59]
	v_mfma_f32_16x16x32_bf16 v[44:47], v[138:141], v[192:195], v[44:47]
	v_mfma_f32_16x16x32_bf16 v[40:43], v[150:153], v[192:195], v[40:43]
	v_mfma_f32_16x16x32_bf16 v[28:31], v[138:141], v[214:217], v[28:31]
	v_mfma_f32_16x16x32_bf16 v[24:27], v[150:153], v[214:217], v[24:27]
	v_mfma_f32_16x16x32_bf16 v[12:15], v[138:141], v[222:225], v[12:15]
	v_mfma_f32_16x16x32_bf16 v[8:11], v[150:153], v[222:225], v[8:11]
	v_mfma_f32_16x16x32_bf16 v[60:63], v[142:145], v[178:181], v[60:63]
	v_mfma_f32_16x16x32_bf16 v[56:59], v[154:157], v[178:181], v[56:59]
	v_mfma_f32_16x16x32_bf16 v[44:47], v[142:145], v[196:199], v[44:47]
	v_mfma_f32_16x16x32_bf16 v[40:43], v[154:157], v[196:199], v[40:43]
	v_mfma_f32_16x16x32_bf16 v[28:31], v[142:145], v[218:221], v[28:31]
	v_mfma_f32_16x16x32_bf16 v[24:27], v[154:157], v[218:221], v[24:27]
	v_mfma_f32_16x16x32_bf16 v[12:15], v[142:145], v[226:229], v[12:15]
	v_mfma_f32_16x16x32_bf16 v[8:11], v[154:157], v[226:229], v[8:11]
	s_setprio 0
	s_setprio 1
	v_mfma_f32_16x16x32_bf16 v[52:55], v[158:161], v[174:177], v[52:55]
	v_mfma_f32_16x16x32_bf16 v[48:51], v[166:169], v[174:177], v[48:51]
	v_mfma_f32_16x16x32_bf16 v[36:39], v[158:161], v[192:195], v[36:39]
	v_mfma_f32_16x16x32_bf16 v[32:35], v[166:169], v[192:195], v[32:35]
	v_mfma_f32_16x16x32_bf16 v[20:23], v[158:161], v[214:217], v[20:23]
	v_mfma_f32_16x16x32_bf16 v[16:19], v[166:169], v[214:217], v[16:19]
	v_mfma_f32_16x16x32_bf16 v[4:7], v[158:161], v[222:225], v[4:7]
	v_mfma_f32_16x16x32_bf16 v[0:3], v[166:169], v[222:225], v[0:3]
	v_mfma_f32_16x16x32_bf16 v[52:55], v[162:165], v[178:181], v[52:55]
	v_mfma_f32_16x16x32_bf16 v[48:51], v[170:173], v[178:181], v[48:51]
	v_mfma_f32_16x16x32_bf16 v[36:39], v[162:165], v[196:199], v[36:39]
	v_mfma_f32_16x16x32_bf16 v[32:35], v[170:173], v[196:199], v[32:35]
	v_mfma_f32_16x16x32_bf16 v[20:23], v[162:165], v[218:221], v[20:23]
	v_mfma_f32_16x16x32_bf16 v[16:19], v[170:173], v[218:221], v[16:19]
	v_mfma_f32_16x16x32_bf16 v[4:7], v[162:165], v[226:229], v[4:7]
	v_mfma_f32_16x16x32_bf16 v[0:3], v[170:173], v[226:229], v[0:3]
	s_setprio 0
	s_barrier
	s_add_i32 s8, 0, 0x18000
	s_add_i32 s20, 0, 0x1c000
	v_add_u32_e32 v154, s8, v147
	v_add_u32_e32 v238, s8, v241
	v_add_u32_e32 v170, s20, v147
	v_add_u32_e32 v239, s20, v241
	ds_read_b128 v[138:141], v154
	ds_read_b128 v[142:145], v238
	ds_read_b128 v[150:153], v154 offset:2048
	ds_read_b128 v[154:157], v238 offset:2048
	ds_read_b128 v[158:161], v170
	ds_read_b128 v[162:165], v239
	ds_read_b128 v[166:169], v170 offset:2048
	ds_read_b128 v[170:173], v239 offset:2048
	s_add_u32 s12, s12, 0x80000
	s_addc_u32 s13, s13, 0
	s_mov_b32 m0, s38
	v_lshl_add_u64 v[230:231], s[12:13], 0, v[132:133]
	ds_read_b128 v[174:177], v149 offset:32768
	ds_read_b128 v[178:181], v240 offset:32768
	ds_read_b128 v[192:195], v149 offset:34816
	ds_read_b128 v[196:199], v240 offset:34816
	ds_read_b128 v[214:217], v149 offset:36864
	ds_read_b128 v[218:221], v240 offset:36864
	ds_read_b128 v[222:225], v149 offset:38912
	ds_read_b128 v[226:229], v240 offset:38912
	global_load_lds_dwordx4 v[230:231], off
	v_lshl_add_u64 v[230:231], s[12:13], 0, v[130:131]
	s_mov_b32 m0, s39
	s_nop 0
	global_load_lds_dwordx4 v[230:231], off
	s_waitcnt vmcnt(8)
	s_waitcnt lgkmcnt(0)
	s_barrier
	s_setprio 1
	s_waitcnt lgkmcnt(0)
	v_mfma_f32_16x16x32_bf16 v[124:127], v[138:141], v[174:177], v[124:127]
	v_mfma_f32_16x16x32_bf16 v[120:123], v[150:153], v[174:177], v[120:123]
	v_mfma_f32_16x16x32_bf16 v[108:111], v[138:141], v[192:195], v[108:111]
	v_mfma_f32_16x16x32_bf16 v[104:107], v[150:153], v[192:195], v[104:107]
	v_mfma_f32_16x16x32_bf16 v[92:95], v[138:141], v[214:217], v[92:95]
	v_mfma_f32_16x16x32_bf16 v[88:91], v[150:153], v[214:217], v[88:91]
	v_mfma_f32_16x16x32_bf16 v[76:79], v[138:141], v[222:225], v[76:79]
	v_mfma_f32_16x16x32_bf16 v[72:75], v[150:153], v[222:225], v[72:75]
	v_mfma_f32_16x16x32_bf16 v[124:127], v[142:145], v[178:181], v[124:127]
	v_mfma_f32_16x16x32_bf16 v[120:123], v[154:157], v[178:181], v[120:123]
	v_mfma_f32_16x16x32_bf16 v[108:111], v[142:145], v[196:199], v[108:111]
	v_mfma_f32_16x16x32_bf16 v[104:107], v[154:157], v[196:199], v[104:107]
	v_mfma_f32_16x16x32_bf16 v[92:95], v[142:145], v[218:221], v[92:95]
	v_mfma_f32_16x16x32_bf16 v[88:91], v[154:157], v[218:221], v[88:91]
	v_mfma_f32_16x16x32_bf16 v[76:79], v[142:145], v[226:229], v[76:79]
	v_mfma_f32_16x16x32_bf16 v[72:75], v[154:157], v[226:229], v[72:75]
	s_setprio 0
	s_setprio 1
	v_mfma_f32_16x16x32_bf16 v[116:119], v[158:161], v[174:177], v[116:119]
	v_mfma_f32_16x16x32_bf16 v[112:115], v[166:169], v[174:177], v[112:115]
	v_mfma_f32_16x16x32_bf16 v[100:103], v[158:161], v[192:195], v[100:103]
	v_mfma_f32_16x16x32_bf16 v[96:99], v[166:169], v[192:195], v[96:99]
	v_mfma_f32_16x16x32_bf16 v[84:87], v[158:161], v[214:217], v[84:87]
	v_mfma_f32_16x16x32_bf16 v[80:83], v[166:169], v[214:217], v[80:83]
	v_mfma_f32_16x16x32_bf16 v[68:71], v[158:161], v[222:225], v[68:71]
	v_mfma_f32_16x16x32_bf16 v[64:67], v[166:169], v[222:225], v[64:67]
	v_mfma_f32_16x16x32_bf16 v[116:119], v[162:165], v[178:181], v[116:119]
	v_mfma_f32_16x16x32_bf16 v[112:115], v[170:173], v[178:181], v[112:115]
	v_mfma_f32_16x16x32_bf16 v[100:103], v[162:165], v[196:199], v[100:103]
	v_mfma_f32_16x16x32_bf16 v[96:99], v[170:173], v[196:199], v[96:99]
	v_mfma_f32_16x16x32_bf16 v[84:87], v[162:165], v[218:221], v[84:87]
	v_mfma_f32_16x16x32_bf16 v[80:83], v[170:173], v[218:221], v[80:83]
	v_mfma_f32_16x16x32_bf16 v[68:71], v[162:165], v[226:229], v[68:71]
	v_mfma_f32_16x16x32_bf16 v[64:67], v[170:173], v[226:229], v[64:67]
	s_setprio 0
	s_barrier
	s_add_i32 s8, s8, s25
	v_lshl_add_u64 v[182:183], v[182:183], 0, s[26:27]
	s_mov_b32 m0, s8
	ds_read_b128 v[174:177], v149 offset:49152
	ds_read_b128 v[178:181], v240 offset:49152
	ds_read_b128 v[192:195], v149 offset:51200
	ds_read_b128 v[196:199], v240 offset:51200
	ds_read_b128 v[214:217], v149 offset:53248
	ds_read_b128 v[218:221], v240 offset:53248
	ds_read_b128 v[222:225], v149 offset:55296
	ds_read_b128 v[226:229], v240 offset:55296
	global_load_lds_dwordx4 v[182:183], off
	s_add_i32 m0, s8, 0x2000
	s_add_u32 s12, s44, 0x80080
	v_lshl_add_u64 v[182:183], v[186:187], 0, s[26:27]
	s_addc_u32 s13, s45, 0
	s_add_i32 s8, s20, s25
	global_load_lds_dwordx4 v[182:183], off
	v_lshl_add_u64 v[182:183], s[12:13], 0, v[184:185]
	s_mov_b32 m0, s8
	s_nop 0
	global_load_lds_dwordx4 v[182:183], off
	v_lshl_add_u64 v[182:183], s[12:13], 0, v[128:129]
	s_add_i32 m0, s8, 0x2000
	s_nop 0
	global_load_lds_dwordx4 v[182:183], off
	v_lshl_add_u64 v[182:183], v[188:189], 0, s[26:27]
	s_mov_b32 m0, s34
	s_nop 0
	global_load_lds_dwordx4 v[182:183], off
	v_lshl_add_u64 v[182:183], v[200:201], 0, s[26:27]
	s_mov_b32 m0, s35
	s_nop 0
	global_load_lds_dwordx4 v[182:183], off
	s_waitcnt vmcnt(8)
	s_waitcnt lgkmcnt(0)
	s_barrier
	s_setprio 1
	s_waitcnt lgkmcnt(0)
	v_mfma_f32_16x16x32_bf16 v[60:63], v[138:141], v[174:177], v[60:63]
	v_mfma_f32_16x16x32_bf16 v[56:59], v[150:153], v[174:177], v[56:59]
	v_mfma_f32_16x16x32_bf16 v[44:47], v[138:141], v[192:195], v[44:47]
	v_mfma_f32_16x16x32_bf16 v[40:43], v[150:153], v[192:195], v[40:43]
	v_mfma_f32_16x16x32_bf16 v[28:31], v[138:141], v[214:217], v[28:31]
	v_mfma_f32_16x16x32_bf16 v[24:27], v[150:153], v[214:217], v[24:27]
	v_mfma_f32_16x16x32_bf16 v[12:15], v[138:141], v[222:225], v[12:15]
	v_mfma_f32_16x16x32_bf16 v[8:11], v[150:153], v[222:225], v[8:11]
	v_mfma_f32_16x16x32_bf16 v[60:63], v[142:145], v[178:181], v[60:63]
	v_mfma_f32_16x16x32_bf16 v[56:59], v[154:157], v[178:181], v[56:59]
	v_mfma_f32_16x16x32_bf16 v[44:47], v[142:145], v[196:199], v[44:47]
	v_mfma_f32_16x16x32_bf16 v[40:43], v[154:157], v[196:199], v[40:43]
	v_mfma_f32_16x16x32_bf16 v[28:31], v[142:145], v[218:221], v[28:31]
	v_mfma_f32_16x16x32_bf16 v[24:27], v[154:157], v[218:221], v[24:27]
	v_mfma_f32_16x16x32_bf16 v[12:15], v[142:145], v[226:229], v[12:15]
	v_mfma_f32_16x16x32_bf16 v[8:11], v[154:157], v[226:229], v[8:11]
	s_setprio 0
	s_setprio 1
	v_mfma_f32_16x16x32_bf16 v[52:55], v[158:161], v[174:177], v[52:55]
	v_mfma_f32_16x16x32_bf16 v[48:51], v[166:169], v[174:177], v[48:51]
	v_mfma_f32_16x16x32_bf16 v[36:39], v[158:161], v[192:195], v[36:39]
	v_mfma_f32_16x16x32_bf16 v[32:35], v[166:169], v[192:195], v[32:35]
	v_mfma_f32_16x16x32_bf16 v[20:23], v[158:161], v[214:217], v[20:23]
	v_mfma_f32_16x16x32_bf16 v[16:19], v[166:169], v[214:217], v[16:19]
	v_mfma_f32_16x16x32_bf16 v[4:7], v[158:161], v[222:225], v[4:7]
	v_mfma_f32_16x16x32_bf16 v[0:3], v[166:169], v[222:225], v[0:3]
	v_mfma_f32_16x16x32_bf16 v[52:55], v[162:165], v[178:181], v[52:55]
	v_mfma_f32_16x16x32_bf16 v[48:51], v[170:173], v[178:181], v[48:51]
	v_mfma_f32_16x16x32_bf16 v[36:39], v[162:165], v[196:199], v[36:39]
	v_mfma_f32_16x16x32_bf16 v[32:35], v[170:173], v[196:199], v[32:35]
	v_mfma_f32_16x16x32_bf16 v[20:23], v[162:165], v[218:221], v[20:23]
	v_mfma_f32_16x16x32_bf16 v[16:19], v[170:173], v[218:221], v[16:19]
	v_mfma_f32_16x16x32_bf16 v[4:7], v[162:165], v[226:229], v[4:7]
	v_mfma_f32_16x16x32_bf16 v[0:3], v[170:173], v[226:229], v[0:3]
	s_setprio 0
	s_barrier
	s_add_i32 s51, s51, 2
	s_add_u32 s14, s14, 0x100
	s_addc_u32 s15, s15, 0
	s_add_u32 s49, s49, 0x100
	s_addc_u32 s50, s50, 0
	s_cmp_gt_u32 s51, 29
	s_cbranch_scc0 .LBB0_182
	s_and_b64 vcc, exec, s[62:63]
	s_cbranch_vccz .LBB0_185
	s_barrier
